# GEMM K-loop: issue the k=0 and k=1 MFMAs of each accumulator back to back (same work, per-accumulator order kept, bit-identical)
# speedup vs baseline: 1.0101x; 1.0101x over previous
; #define PG8_STAGE(bufoff, gbase, voff) do { _Pragma("unroll") for (int _i = 0; _i < 2; ++_i) \
;         __builtin_amdgcn_global_load_lds((const unsigned*)((const char*)(gbase) + (voff)[_i]), (PG8_LAS unsigned*)(lds + (bufoff) + ldsw + _i * 8192), 16, 0, 0); } while (0)
; #define PG8_LDA(dst, b, h) do { _Pragma("unroll") for (int m = 0; m < 4; ++m) _Pragma("unroll") for (int k = 0; k < 2; ++k) dst[m][k] = *(const PG8_LAS bf16x8*)(lds + PG8_SA(b, h) + aoff + m * 2048 + k * 1024); } while (0)
; #define PG8_LDB(dst, b, h) do { _Pragma("unroll") for (int n = 0; n < 2; ++n) _Pragma("unroll") for (int k = 0; k < 2; ++k) dst[n][k] = *(const PG8_LAS bf16x8*)(lds + PG8_SB(b, h) + boff + n * 2048 + k * 1024); } while (0)
; #define PG8_MMA(ai, bj, At, Bt) do { __builtin_amdgcn_s_setprio(1); _Pragma("unroll") for (int m = 0; m < 4; ++m) _Pragma("unroll") for (int n = 0; n < 2; ++n) _Pragma("unroll") for (int k = 0; k < 2; ++k) \
;         acc[ai][bj][m][n] = __builtin_amdgcn_mfma_f32_16x16x32_bf16(Bt[n][k], At[m][k], acc[ai][bj][m][n], 0, 0, 0); __builtin_amdgcn_s_setprio(0); } while (0)
; #define PG8_WAIT_V(n) asm volatile("s_waitcnt vmcnt(" #n ")" ::: "memory")
; #define PG8_WAIT_L(n) asm volatile("s_waitcnt lgkmcnt(" #n ")" ::: "memory")
; #define PG8_BAR __builtin_amdgcn_s_barrier()
; #define PG8_SCHED __builtin_amdgcn_sched_barrier(0)
; template <class Epi, class Sched, bool ALIGN_EPI = false, bool SP2 = false>
; __device__ __forceinline__ void gemm_phase(PG8_LAS unsigned char* lds, const Gemm g, const Sched& S, const Epi& E) {
;     ...
;             PG8_LDB(B0, 0, 0); PG8_LDB(B1, 0, 1); PG8_SCHED; PG8_LDA(At, 0, 0); PG8_STAGE(PG8_SA(1, 1), a1 + hstep, voffA);
;             PG8_WAIT_V(8); PG8_WAIT_L(0); PG8_BAR; PG8_MMA(0, 0, At, B0); PG8_MMA(0, 1, At, B1); PG8_BAR; PG8_SCHED;
;             PG8_LDA(At, 0, 1); PG8_STAGE(PG8_SB(0, 0), b2, voffB); PG8_STAGE(PG8_SB(0, 1), b2 + hstep, voffB); PG8_STAGE(PG8_SA(0, 0), a2, voffA);
;             PG8_WAIT_V(8); PG8_WAIT_L(0); PG8_BAR; PG8_MMA(1, 0, At, B0); PG8_MMA(1, 1, At, B1); PG8_BAR; PG8_SCHED;
.LBB0_322:
	s_add_i32 s42, s14, 2
	s_add_u32 s43, s12, 0x80
	s_addc_u32 s15, s13, 0
	s_add_i32 s75, 0, 0x10000
	s_cmp_eq_u32 s25, s14
	s_cselect_b32 s15, s55, s15
	s_cselect_b32 s14, s54, s43
	s_cselect_b32 vcc_hi, s65, s17
	s_cselect_b32 vcc_lo, s64, s16
	s_add_i32 s43, 0, 0x14000
	v_add_u32_e32 v142, s75, v199
	v_add_u32_e32 v178, s43, v199
	ds_read_b128 v[130:133], v142
	ds_read_b128 v[134:137], v142 offset:1024
	ds_read_b128 v[138:141], v142 offset:2048
	ds_read_b128 v[142:145], v142 offset:3072
	ds_read_b128 v[170:173], v178
	ds_read_b128 v[174:177], v178 offset:1024
	ds_read_b128 v[202:205], v178 offset:2048
	ds_read_b128 v[206:209], v178 offset:3072
	v_lshl_add_u64 v[178:179], s[12:13], 0, v[166:167]
	s_add_i32 m0, s56, 0xc000
	ds_read_b128 v[210:213], v201
	ds_read_b128 v[214:217], v201 offset:1024
	ds_read_b128 v[218:221], v201 offset:2048
	ds_read_b128 v[222:225], v201 offset:3072
	ds_read_b128 v[226:229], v201 offset:4096
	ds_read_b128 v[230:233], v201 offset:5120
	ds_read_b128 v[234:237], v201 offset:6144
	ds_read_b128 v[238:241], v201 offset:7168
	global_load_lds_dwordx4 v[178:179], off
	v_lshl_add_u64 v[178:179], s[12:13], 0, v[168:169]
	s_add_i32 m0, s56, 0xe000
	s_nop 0
	global_load_lds_dwordx4 v[178:179], off
	s_waitcnt vmcnt(8)
	s_waitcnt lgkmcnt(0)
	s_barrier
	s_setprio 1
	s_waitcnt lgkmcnt(0)
	v_mfma_f32_16x16x32_bf16 v[126:129], v[130:133], v[210:213], v[126:129]
	v_mfma_f32_16x16x32_bf16 v[126:129], v[134:137], v[214:217], v[126:129]
	v_mfma_f32_16x16x32_bf16 v[122:125], v[138:141], v[210:213], v[122:125]
	v_mfma_f32_16x16x32_bf16 v[122:125], v[142:145], v[214:217], v[122:125]
	v_mfma_f32_16x16x32_bf16 v[110:113], v[130:133], v[218:221], v[110:113]
	v_mfma_f32_16x16x32_bf16 v[110:113], v[134:137], v[222:225], v[110:113]
	v_mfma_f32_16x16x32_bf16 v[106:109], v[138:141], v[218:221], v[106:109]
	v_mfma_f32_16x16x32_bf16 v[106:109], v[142:145], v[222:225], v[106:109]
	v_mfma_f32_16x16x32_bf16 v[94:97], v[130:133], v[226:229], v[94:97]
	v_mfma_f32_16x16x32_bf16 v[94:97], v[134:137], v[230:233], v[94:97]
	v_mfma_f32_16x16x32_bf16 v[90:93], v[138:141], v[226:229], v[90:93]
	v_mfma_f32_16x16x32_bf16 v[90:93], v[142:145], v[230:233], v[90:93]
	v_mfma_f32_16x16x32_bf16 v[78:81], v[130:133], v[234:237], v[78:81]
	v_mfma_f32_16x16x32_bf16 v[78:81], v[134:137], v[238:241], v[78:81]
	v_mfma_f32_16x16x32_bf16 v[74:77], v[138:141], v[234:237], v[74:77]
	v_mfma_f32_16x16x32_bf16 v[74:77], v[142:145], v[238:241], v[74:77]
	s_setprio 0
	s_setprio 1
	v_mfma_f32_16x16x32_bf16 v[118:121], v[170:173], v[210:213], v[118:121]
	v_mfma_f32_16x16x32_bf16 v[118:121], v[174:177], v[214:217], v[118:121]
	v_mfma_f32_16x16x32_bf16 v[114:117], v[202:205], v[210:213], v[114:117]
	v_mfma_f32_16x16x32_bf16 v[114:117], v[206:209], v[214:217], v[114:117]
	v_mfma_f32_16x16x32_bf16 v[102:105], v[170:173], v[218:221], v[102:105]
	v_mfma_f32_16x16x32_bf16 v[102:105], v[174:177], v[222:225], v[102:105]
	v_mfma_f32_16x16x32_bf16 v[98:101], v[202:205], v[218:221], v[98:101]
	v_mfma_f32_16x16x32_bf16 v[98:101], v[206:209], v[222:225], v[98:101]
	v_mfma_f32_16x16x32_bf16 v[86:89], v[170:173], v[226:229], v[86:89]
	v_mfma_f32_16x16x32_bf16 v[86:89], v[174:177], v[230:233], v[86:89]
	v_mfma_f32_16x16x32_bf16 v[82:85], v[202:205], v[226:229], v[82:85]
	v_mfma_f32_16x16x32_bf16 v[82:85], v[206:209], v[230:233], v[82:85]
	v_mfma_f32_16x16x32_bf16 v[70:73], v[170:173], v[234:237], v[70:73]
	v_mfma_f32_16x16x32_bf16 v[70:73], v[174:177], v[238:241], v[70:73]
	v_mfma_f32_16x16x32_bf16 v[66:69], v[202:205], v[234:237], v[66:69]
	v_mfma_f32_16x16x32_bf16 v[66:69], v[206:209], v[238:241], v[66:69]
	s_setprio 0
	s_barrier
	s_add_i32 s75, s75, s23
	v_lshl_add_u64 v[178:179], vcc, 0, v[0:1]
	s_mov_b32 m0, s75
	ds_read_b128 v[210:213], v201 offset:16384
	ds_read_b128 v[214:217], v201 offset:17408
	ds_read_b128 v[218:221], v201 offset:18432
	ds_read_b128 v[222:225], v201 offset:19456
	ds_read_b128 v[226:229], v201 offset:20480
	ds_read_b128 v[230:233], v201 offset:21504
	ds_read_b128 v[234:237], v201 offset:22528
	ds_read_b128 v[238:241], v201 offset:23552
	global_load_lds_dwordx4 v[178:179], off
	s_add_i32 m0, s75, 0x2000
	v_lshl_add_u64 v[242:243], vcc, 0, v[162:163]
	s_add_u32 vcc_lo, vcc_lo, s84
	s_addc_u32 vcc_hi, vcc_hi, 0
	s_add_i32 s43, s43, s23
	global_load_lds_dwordx4 v[242:243], off
	v_lshl_add_u64 v[244:245], vcc, 0, v[0:1]
	s_mov_b32 m0, s43
	v_lshl_add_u64 v[246:247], vcc, 0, v[162:163]
	global_load_lds_dwordx4 v[244:245], off
	s_add_i32 m0, s43, 0x2000
	v_lshl_add_u64 v[248:249], s[14:15], 0, v[158:159]
	global_load_lds_dwordx4 v[246:247], off
	s_mov_b32 m0, s56
	v_lshl_add_u64 v[250:251], s[14:15], 0, v[160:161]
	global_load_lds_dwordx4 v[248:249], off
	s_mov_b32 m0, s82
	s_nop 0
	global_load_lds_dwordx4 v[250:251], off
	s_waitcnt vmcnt(8)
	s_waitcnt lgkmcnt(0)
	s_barrier
; #define PG8_STAGE(bufoff, gbase, voff) do { _Pragma("unroll") for (int _i = 0; _i < 2; ++_i) \
;         __builtin_amdgcn_global_load_lds((const unsigned*)((const char*)(gbase) + (voff)[_i]), (PG8_LAS unsigned*)(lds + (bufoff) + ldsw + _i * 8192), 16, 0, 0); } while (0)
; #define PG8_LDA(dst, b, h) do { _Pragma("unroll") for (int m = 0; m < 4; ++m) _Pragma("unroll") for (int k = 0; k < 2; ++k) dst[m][k] = *(const PG8_LAS bf16x8*)(lds + PG8_SA(b, h) + aoff + m * 2048 + k * 1024); } while (0)
; #define PG8_LDB(dst, b, h) do { _Pragma("unroll") for (int n = 0; n < 2; ++n) _Pragma("unroll") for (int k = 0; k < 2; ++k) dst[n][k] = *(const PG8_LAS bf16x8*)(lds + PG8_SB(b, h) + boff + n * 2048 + k * 1024); } while (0)
; #define PG8_MMA(ai, bj, At, Bt) do { __builtin_amdgcn_s_setprio(1); _Pragma("unroll") for (int m = 0; m < 4; ++m) _Pragma("unroll") for (int n = 0; n < 2; ++n) _Pragma("unroll") for (int k = 0; k < 2; ++k) \
;         acc[ai][bj][m][n] = __builtin_amdgcn_mfma_f32_16x16x32_bf16(Bt[n][k], At[m][k], acc[ai][bj][m][n], 0, 0, 0); __builtin_amdgcn_s_setprio(0); } while (0)
; #define PG8_WAIT_V(n) asm volatile("s_waitcnt vmcnt(" #n ")" ::: "memory")
; #define PG8_WAIT_L(n) asm volatile("s_waitcnt lgkmcnt(" #n ")" ::: "memory")
; #define PG8_BAR __builtin_amdgcn_s_barrier()
; #define PG8_SCHED __builtin_amdgcn_sched_barrier(0)
; template <class Epi, class Sched, bool ALIGN_EPI = false, bool SP2 = false>
; __device__ __forceinline__ void gemm_phase(PG8_LAS unsigned char* lds, const Gemm g, const Sched& S, const Epi& E) {
;     ...
;             PG8_WAIT_V(8); PG8_WAIT_L(0); PG8_BAR; PG8_MMA(1, 0, At, B0); PG8_MMA(1, 1, At, B1); PG8_BAR; PG8_SCHED;
;             PG8_LDB(B0, 1, 0); PG8_LDB(B1, 1, 1); PG8_SCHED; PG8_LDA(At, 1, 0); PG8_STAGE(PG8_SA(0, 1), a2 + hstep, voffA);
;             PG8_WAIT_V(8); PG8_WAIT_L(0); PG8_BAR; PG8_MMA(0, 0, At, B0); PG8_MMA(0, 1, At, B1); PG8_BAR; PG8_SCHED;
	s_setprio 1
	s_waitcnt lgkmcnt(0)
	v_mfma_f32_16x16x32_bf16 v[62:65], v[130:133], v[210:213], v[62:65]
	v_mfma_f32_16x16x32_bf16 v[62:65], v[134:137], v[214:217], v[62:65]
	v_mfma_f32_16x16x32_bf16 v[58:61], v[138:141], v[210:213], v[58:61]
	v_mfma_f32_16x16x32_bf16 v[58:61], v[142:145], v[214:217], v[58:61]
	v_mfma_f32_16x16x32_bf16 v[46:49], v[130:133], v[218:221], v[46:49]
	v_mfma_f32_16x16x32_bf16 v[46:49], v[134:137], v[222:225], v[46:49]
	v_mfma_f32_16x16x32_bf16 v[42:45], v[138:141], v[218:221], v[42:45]
	v_mfma_f32_16x16x32_bf16 v[42:45], v[142:145], v[222:225], v[42:45]
	v_mfma_f32_16x16x32_bf16 v[30:33], v[130:133], v[226:229], v[30:33]
	v_mfma_f32_16x16x32_bf16 v[30:33], v[134:137], v[230:233], v[30:33]
	v_mfma_f32_16x16x32_bf16 v[26:29], v[138:141], v[226:229], v[26:29]
	v_mfma_f32_16x16x32_bf16 v[26:29], v[142:145], v[230:233], v[26:29]
	v_mfma_f32_16x16x32_bf16 v[14:17], v[130:133], v[234:237], v[14:17]
	v_mfma_f32_16x16x32_bf16 v[14:17], v[134:137], v[238:241], v[14:17]
	v_mfma_f32_16x16x32_bf16 v[10:13], v[138:141], v[234:237], v[10:13]
	v_mfma_f32_16x16x32_bf16 v[10:13], v[142:145], v[238:241], v[10:13]
	s_setprio 0
	s_setprio 1
	v_mfma_f32_16x16x32_bf16 v[54:57], v[170:173], v[210:213], v[54:57]
	v_mfma_f32_16x16x32_bf16 v[54:57], v[174:177], v[214:217], v[54:57]
	v_mfma_f32_16x16x32_bf16 v[50:53], v[202:205], v[210:213], v[50:53]
	v_mfma_f32_16x16x32_bf16 v[50:53], v[206:209], v[214:217], v[50:53]
	v_mfma_f32_16x16x32_bf16 v[38:41], v[170:173], v[218:221], v[38:41]
	v_mfma_f32_16x16x32_bf16 v[38:41], v[174:177], v[222:225], v[38:41]
	v_mfma_f32_16x16x32_bf16 v[34:37], v[202:205], v[218:221], v[34:37]
	v_mfma_f32_16x16x32_bf16 v[34:37], v[206:209], v[222:225], v[34:37]
	v_mfma_f32_16x16x32_bf16 v[22:25], v[170:173], v[226:229], v[22:25]
	v_mfma_f32_16x16x32_bf16 v[22:25], v[174:177], v[230:233], v[22:25]
	v_mfma_f32_16x16x32_bf16 v[18:21], v[202:205], v[226:229], v[18:21]
	v_mfma_f32_16x16x32_bf16 v[18:21], v[206:209], v[230:233], v[18:21]
	v_mfma_f32_16x16x32_bf16 v[6:9], v[170:173], v[234:237], v[6:9]
	v_mfma_f32_16x16x32_bf16 v[6:9], v[174:177], v[238:241], v[6:9]
	v_mfma_f32_16x16x32_bf16 v[2:5], v[202:205], v[234:237], v[2:5]
	v_mfma_f32_16x16x32_bf16 v[2:5], v[206:209], v[238:241], v[2:5]
	s_setprio 0
	s_barrier
	s_add_i32 s43, 0, 0x18000
	s_add_i32 s75, 0, 0x1c000
	v_add_u32_e32 v142, s43, v199
	v_add_u32_e32 v206, s75, v199
	ds_read_b128 v[130:133], v142
	ds_read_b128 v[134:137], v142 offset:1024
	ds_read_b128 v[138:141], v142 offset:2048
	ds_read_b128 v[142:145], v142 offset:3072
	ds_read_b128 v[170:173], v206
	ds_read_b128 v[174:177], v206 offset:1024
	ds_read_b128 v[202:205], v206 offset:2048
	ds_read_b128 v[206:209], v206 offset:3072
	s_add_u32 s14, s14, s84
	s_addc_u32 s15, s15, 0
	s_mov_b32 m0, s83
	v_lshl_add_u64 v[252:253], s[14:15], 0, v[158:159]
	ds_read_b128 v[210:213], v201 offset:32768
	ds_read_b128 v[214:217], v201 offset:33792
	ds_read_b128 v[218:221], v201 offset:34816
	ds_read_b128 v[222:225], v201 offset:35840
	ds_read_b128 v[226:229], v201 offset:36864
	ds_read_b128 v[230:233], v201 offset:37888
	ds_read_b128 v[234:237], v201 offset:38912
	ds_read_b128 v[238:241], v201 offset:39936
	global_load_lds_dwordx4 v[252:253], off
	v_lshl_add_u64 v[252:253], s[14:15], 0, v[160:161]
	s_mov_b32 m0, s24
	s_nop 0
	global_load_lds_dwordx4 v[252:253], off
	s_waitcnt vmcnt(8)
	s_waitcnt lgkmcnt(0)
	s_barrier
	s_setprio 1
	s_waitcnt lgkmcnt(0)
	v_mfma_f32_16x16x32_bf16 v[126:129], v[130:133], v[210:213], v[126:129]
	v_mfma_f32_16x16x32_bf16 v[126:129], v[134:137], v[214:217], v[126:129]
	v_mfma_f32_16x16x32_bf16 v[122:125], v[138:141], v[210:213], v[122:125]
	v_mfma_f32_16x16x32_bf16 v[122:125], v[142:145], v[214:217], v[122:125]
	v_mfma_f32_16x16x32_bf16 v[110:113], v[130:133], v[218:221], v[110:113]
	v_mfma_f32_16x16x32_bf16 v[110:113], v[134:137], v[222:225], v[110:113]
	v_mfma_f32_16x16x32_bf16 v[106:109], v[138:141], v[218:221], v[106:109]
	v_mfma_f32_16x16x32_bf16 v[106:109], v[142:145], v[222:225], v[106:109]
	v_mfma_f32_16x16x32_bf16 v[94:97], v[130:133], v[226:229], v[94:97]
	v_mfma_f32_16x16x32_bf16 v[94:97], v[134:137], v[230:233], v[94:97]
	v_mfma_f32_16x16x32_bf16 v[90:93], v[138:141], v[226:229], v[90:93]
	v_mfma_f32_16x16x32_bf16 v[90:93], v[142:145], v[230:233], v[90:93]
	v_mfma_f32_16x16x32_bf16 v[78:81], v[130:133], v[234:237], v[78:81]
	v_mfma_f32_16x16x32_bf16 v[78:81], v[134:137], v[238:241], v[78:81]
	v_mfma_f32_16x16x32_bf16 v[74:77], v[138:141], v[234:237], v[74:77]
	v_mfma_f32_16x16x32_bf16 v[74:77], v[142:145], v[238:241], v[74:77]
	s_setprio 0
	s_setprio 1
	v_mfma_f32_16x16x32_bf16 v[118:121], v[170:173], v[210:213], v[118:121]
	v_mfma_f32_16x16x32_bf16 v[118:121], v[174:177], v[214:217], v[118:121]
	v_mfma_f32_16x16x32_bf16 v[114:117], v[202:205], v[210:213], v[114:117]
	v_mfma_f32_16x16x32_bf16 v[114:117], v[206:209], v[214:217], v[114:117]
	v_mfma_f32_16x16x32_bf16 v[102:105], v[170:173], v[218:221], v[102:105]
	v_mfma_f32_16x16x32_bf16 v[102:105], v[174:177], v[222:225], v[102:105]
	v_mfma_f32_16x16x32_bf16 v[98:101], v[202:205], v[218:221], v[98:101]
	v_mfma_f32_16x16x32_bf16 v[98:101], v[206:209], v[222:225], v[98:101]
	v_mfma_f32_16x16x32_bf16 v[86:89], v[170:173], v[226:229], v[86:89]
	v_mfma_f32_16x16x32_bf16 v[86:89], v[174:177], v[230:233], v[86:89]
	v_mfma_f32_16x16x32_bf16 v[82:85], v[202:205], v[226:229], v[82:85]
	v_mfma_f32_16x16x32_bf16 v[82:85], v[206:209], v[230:233], v[82:85]
	v_mfma_f32_16x16x32_bf16 v[70:73], v[170:173], v[234:237], v[70:73]
	v_mfma_f32_16x16x32_bf16 v[70:73], v[174:177], v[238:241], v[70:73]
	v_mfma_f32_16x16x32_bf16 v[66:69], v[202:205], v[234:237], v[66:69]
	v_mfma_f32_16x16x32_bf16 v[66:69], v[206:209], v[238:241], v[66:69]
	s_setprio 0
	s_barrier
; #define PG8_STAGE(bufoff, gbase, voff) do { _Pragma("unroll") for (int _i = 0; _i < 2; ++_i) \
;         __builtin_amdgcn_global_load_lds((const unsigned*)((const char*)(gbase) + (voff)[_i]), (PG8_LAS unsigned*)(lds + (bufoff) + ldsw + _i * 8192), 16, 0, 0); } while (0)
; #define PG8_LDA(dst, b, h) do { _Pragma("unroll") for (int m = 0; m < 4; ++m) _Pragma("unroll") for (int k = 0; k < 2; ++k) dst[m][k] = *(const PG8_LAS bf16x8*)(lds + PG8_SA(b, h) + aoff + m * 2048 + k * 1024); } while (0)
; #define PG8_MMA(ai, bj, At, Bt) do { __builtin_amdgcn_s_setprio(1); _Pragma("unroll") for (int m = 0; m < 4; ++m) _Pragma("unroll") for (int n = 0; n < 2; ++n) _Pragma("unroll") for (int k = 0; k < 2; ++k) \
;         acc[ai][bj][m][n] = __builtin_amdgcn_mfma_f32_16x16x32_bf16(Bt[n][k], At[m][k], acc[ai][bj][m][n], 0, 0, 0); __builtin_amdgcn_s_setprio(0); } while (0)
; #define PG8_WAIT_V(n) asm volatile("s_waitcnt vmcnt(" #n ")" ::: "memory")
; #define PG8_WAIT_L(n) asm volatile("s_waitcnt lgkmcnt(" #n ")" ::: "memory")
; #define PG8_BAR __builtin_amdgcn_s_barrier()
; #define PG8_SCHED __builtin_amdgcn_sched_barrier(0)
; template <class Epi, class Sched, bool ALIGN_EPI = false, bool SP2 = false>
; __device__ __forceinline__ void gemm_phase(PG8_LAS unsigned char* lds, const Gemm g, const Sched& S, const Epi& E) {
;     ...
;         for (int t = 0; t < nt; t += 2) {
;     ...
;             PG8_LDA(At, 1, 1); PG8_STAGE(PG8_SB(1, 0), b3, voffB); PG8_STAGE(PG8_SB(1, 1), b3 + hstep, voffB); PG8_STAGE(PG8_SA(1, 0), a3, voffA);
;             PG8_WAIT_V(8); PG8_WAIT_L(0); PG8_BAR; PG8_MMA(1, 0, At, B0); PG8_MMA(1, 1, At, B1); PG8_BAR; PG8_SCHED;
	s_add_i32 s14, s43, s23
	v_lshl_add_u64 v[178:179], v[178:179], 0, s[94:95]
	s_mov_b32 m0, s14
	ds_read_b128 v[210:213], v201 offset:49152
	ds_read_b128 v[214:217], v201 offset:50176
	ds_read_b128 v[218:221], v201 offset:51200
	ds_read_b128 v[222:225], v201 offset:52224
	ds_read_b128 v[226:229], v201 offset:53248
	ds_read_b128 v[230:233], v201 offset:54272
	ds_read_b128 v[234:237], v201 offset:55296
	ds_read_b128 v[238:241], v201 offset:56320
	global_load_lds_dwordx4 v[178:179], off
	v_lshl_add_u64 v[178:179], v[242:243], 0, s[94:95]
	s_add_i32 m0, s14, 0x2000
	s_add_i32 s14, s75, s23
	global_load_lds_dwordx4 v[178:179], off
	v_lshl_add_u64 v[178:179], v[244:245], 0, s[94:95]
	s_mov_b32 m0, s14
	s_nop 0
	global_load_lds_dwordx4 v[178:179], off
	v_lshl_add_u64 v[178:179], v[246:247], 0, s[94:95]
	s_add_i32 m0, s14, 0x2000
	s_nop 0
	global_load_lds_dwordx4 v[178:179], off
	v_lshl_add_u64 v[178:179], v[248:249], 0, s[94:95]
	s_mov_b32 m0, s63
	s_nop 0
	global_load_lds_dwordx4 v[178:179], off
	v_lshl_add_u64 v[178:179], v[250:251], 0, s[94:95]
	s_mov_b32 m0, s70
	s_nop 0
	global_load_lds_dwordx4 v[178:179], off
	s_waitcnt vmcnt(8)
	s_waitcnt lgkmcnt(0)
	s_barrier
	s_setprio 1
	s_waitcnt lgkmcnt(0)
	v_mfma_f32_16x16x32_bf16 v[62:65], v[130:133], v[210:213], v[62:65]
	v_mfma_f32_16x16x32_bf16 v[62:65], v[134:137], v[214:217], v[62:65]
	v_mfma_f32_16x16x32_bf16 v[58:61], v[138:141], v[210:213], v[58:61]
	v_mfma_f32_16x16x32_bf16 v[58:61], v[142:145], v[214:217], v[58:61]
	v_mfma_f32_16x16x32_bf16 v[46:49], v[130:133], v[218:221], v[46:49]
	v_mfma_f32_16x16x32_bf16 v[46:49], v[134:137], v[222:225], v[46:49]
	v_mfma_f32_16x16x32_bf16 v[42:45], v[138:141], v[218:221], v[42:45]
	v_mfma_f32_16x16x32_bf16 v[42:45], v[142:145], v[222:225], v[42:45]
	v_mfma_f32_16x16x32_bf16 v[30:33], v[130:133], v[226:229], v[30:33]
	v_mfma_f32_16x16x32_bf16 v[30:33], v[134:137], v[230:233], v[30:33]
	v_mfma_f32_16x16x32_bf16 v[26:29], v[138:141], v[226:229], v[26:29]
	v_mfma_f32_16x16x32_bf16 v[26:29], v[142:145], v[230:233], v[26:29]
	v_mfma_f32_16x16x32_bf16 v[14:17], v[130:133], v[234:237], v[14:17]
	v_mfma_f32_16x16x32_bf16 v[14:17], v[134:137], v[238:241], v[14:17]
	v_mfma_f32_16x16x32_bf16 v[10:13], v[138:141], v[234:237], v[10:13]
	v_mfma_f32_16x16x32_bf16 v[10:13], v[142:145], v[238:241], v[10:13]
	s_setprio 0
	s_setprio 1
	v_mfma_f32_16x16x32_bf16 v[54:57], v[170:173], v[210:213], v[54:57]
	v_mfma_f32_16x16x32_bf16 v[54:57], v[174:177], v[214:217], v[54:57]
	v_mfma_f32_16x16x32_bf16 v[50:53], v[202:205], v[210:213], v[50:53]
	v_mfma_f32_16x16x32_bf16 v[50:53], v[206:209], v[214:217], v[50:53]
	v_mfma_f32_16x16x32_bf16 v[38:41], v[170:173], v[218:221], v[38:41]
	v_mfma_f32_16x16x32_bf16 v[38:41], v[174:177], v[222:225], v[38:41]
	v_mfma_f32_16x16x32_bf16 v[34:37], v[202:205], v[218:221], v[34:37]
	v_mfma_f32_16x16x32_bf16 v[34:37], v[206:209], v[222:225], v[34:37]
	v_mfma_f32_16x16x32_bf16 v[22:25], v[170:173], v[226:229], v[22:25]
	v_mfma_f32_16x16x32_bf16 v[22:25], v[174:177], v[230:233], v[22:25]
	v_mfma_f32_16x16x32_bf16 v[18:21], v[202:205], v[226:229], v[18:21]
	v_mfma_f32_16x16x32_bf16 v[18:21], v[206:209], v[230:233], v[18:21]
	v_mfma_f32_16x16x32_bf16 v[6:9], v[170:173], v[234:237], v[6:9]
	v_mfma_f32_16x16x32_bf16 v[6:9], v[174:177], v[238:241], v[6:9]
	v_mfma_f32_16x16x32_bf16 v[2:5], v[202:205], v[234:237], v[2:5]
	v_mfma_f32_16x16x32_bf16 v[2:5], v[206:209], v[238:241], v[2:5]
	s_setprio 0
	s_barrier
	s_add_u32 s12, s12, 0x100
	s_addc_u32 s13, s13, 0
	s_add_u32 s16, s16, 0x100
	s_addc_u32 s17, s17, 0
	s_cmp_ge_u32 s42, s28
	s_mov_b32 s14, s42
	s_cbranch_scc0 .LBB0_322
	s_and_b64 vcc, exec, s[48:49]
	s_cbranch_vccnz .LBB0_326
	v_lshl_add_u32 v170, s72, 8, v157
	s_cmp_lt_i32 s57, 1
	s_mov_b64 s[12:13], -1
	s_cbranch_scc0 .LBB0_327
